# GEMM loops (all but hgin): whole K-tile's fragments prefetched into spare VGPRs so the LDS rewrite for the next K-tile runs under the second k-step's MFMAs
# baseline (speedup 1.0000x reference)
; DEV f32x4 mfma16(bf16x8 a, bf16x8 b, f32x4 c) { return __builtin_amdgcn_mfma_f32_16x16x32_bf16(a, b, c, 0, 0, 0); }
; #define G_LOAD(RA, RB, KT) { _Pragma("unroll") for (int i = 0; i < 4; i++) { \
;       RA[i] = *(const u32x4*)(Ap + (size_t)(i * 32) * lda + (KT) * 64); RB[i] = *(const u32x4*)(Bp + (size_t)(i * 32) * ldb + (KT) * 64); } }
; template <int TI, int TJ, int KS>
; DEV void mfma_lds(const bf16_t* Arows, int lda, const bf16_t* Brows, int ldb, int i0, int j0, f32x4 (&acc)[TI][TJ]) {
;     ...
;   for (int ks = 0; ks < KS; ks++) {
;     bf16x8 af[TI], bfr[TJ];
; #pragma unroll
;     for (int i = 0; i < TI; i++) af[i] = *(const bf16x8*)(Arows + (i0 + i * 16 + l15) * lda + ks * 32 + quad * 8);
; #pragma unroll
;     for (int j = 0; j < TJ; j++) bfr[j] = *(const bf16x8*)(Brows + (j0 + j * 16 + l15) * ldb + ks * 32 + quad * 8);
; #pragma unroll
;     for (int i = 0; i < TI; i++)
; #pragma unroll
;       for (int j = 0; j < TJ; j++) acc[i][j] = mfma16(af[i], bfr[j], acc[i][j]);
; template <class Epi>
; DEV void gemm_tile(const bf16_t* __restrict__ A, int lda, const bf16_t* __restrict__ Bt, int ldb, int K, int m0, int n0,
;                    Epi& epi, char* smem) {
;     ...
;     if (kt + 3 < nk) G_LOAD(ra1, rb1, kt + 3);
;     mfma_lds<4, 4, 2>(Bs, GLD, As, GLD, wn * 64, wm * 64, acc);
.LBB0_181:
	v_mov_b32_e32 v130, v195
	v_and_b32_e32 v135, 15, v130
	v_or_b32_e32 v131, v135, v144
	v_and_b32_e32 v148, 48, v130
	v_mul_u32_u24_e32 v130, 0x50, v131
	v_lshl_add_u32 v147, v130, 1, v148
	v_or_b32_e32 v135, v135, v146
	v_mad_u32_u24 v249, v135, s36, v148
	v_lshl_add_u64 v[136:137], v[136:137], 0, s[34:35]
	v_lshl_add_u64 v[138:139], v[138:139], 0, s[34:35]
	s_andn2_b64 vcc, exec, s[14:15]
	ds_read_b128 v[148:151], v147 offset:20480
	ds_read_b128 v[164:167], v249
	ds_read_b128 v[168:171], v249 offset:2560
	ds_read_b128 v[172:175], v249 offset:5120
	ds_read_b128 v[176:179], v249 offset:7680
	ds_read_b128 v[152:155], v147 offset:23040
	ds_read_b128 v[156:159], v147 offset:25600
	ds_read_b128 v[160:163], v147 offset:28160
	ds_read_b128 v[180:183], v249 offset:64
	ds_read_b128 v[184:187], v249 offset:2624
	ds_read_b128 v[188:191], v249 offset:5184
	ds_read_b128 v[236:239], v249 offset:7744
	ds_read_b128 v[240:243], v147 offset:20544
	ds_read_b128 v[244:247], v147 offset:23104
	s_waitcnt lgkmcnt(12)
	v_mfma_f32_16x16x32_bf16 v[106:109], v[148:151], v[164:167], v[106:109]
	s_waitcnt lgkmcnt(11)
	v_mfma_f32_16x16x32_bf16 v[122:125], v[148:151], v[168:171], v[122:125]
	s_waitcnt lgkmcnt(10)
	v_mfma_f32_16x16x32_bf16 v[114:117], v[148:151], v[172:175], v[114:117]
	s_waitcnt lgkmcnt(9)
	v_mfma_f32_16x16x32_bf16 v[110:113], v[148:151], v[176:179], v[110:113]
	ds_read_b128 v[148:151], v147 offset:25664
	s_waitcnt lgkmcnt(9)
	v_mfma_f32_16x16x32_bf16 v[102:105], v[152:155], v[164:167], v[102:105]
	v_mfma_f32_16x16x32_bf16 v[94:97], v[152:155], v[168:171], v[94:97]
	v_mfma_f32_16x16x32_bf16 v[86:89], v[152:155], v[172:175], v[86:89]
	v_mfma_f32_16x16x32_bf16 v[78:81], v[152:155], v[176:179], v[78:81]
	ds_read_b128 v[152:155], v147 offset:28224
	s_waitcnt lgkmcnt(9)
	v_mfma_f32_16x16x32_bf16 v[82:85], v[156:159], v[164:167], v[82:85]
	v_mfma_f32_16x16x32_bf16 v[74:77], v[156:159], v[168:171], v[74:77]
	v_mfma_f32_16x16x32_bf16 v[70:73], v[156:159], v[172:175], v[70:73]
	v_mfma_f32_16x16x32_bf16 v[66:69], v[156:159], v[176:179], v[66:69]
	s_waitcnt lgkmcnt(8)
	v_mfma_f32_16x16x32_bf16 v[98:101], v[160:163], v[164:167], v[98:101]
	v_mfma_f32_16x16x32_bf16 v[90:93], v[160:163], v[168:171], v[90:93]
	v_mfma_f32_16x16x32_bf16 v[126:129], v[160:163], v[172:175], v[126:129]
	v_mfma_f32_16x16x32_bf16 v[118:121], v[160:163], v[176:179], v[118:121]
	s_waitcnt lgkmcnt(0)
	v_mfma_f32_16x16x32_bf16 v[106:109], v[240:243], v[180:183], v[106:109]
	v_mfma_f32_16x16x32_bf16 v[122:125], v[240:243], v[184:187], v[122:125]
	v_mfma_f32_16x16x32_bf16 v[114:117], v[240:243], v[188:191], v[114:117]
	v_mfma_f32_16x16x32_bf16 v[110:113], v[240:243], v[236:239], v[110:113]
	v_mfma_f32_16x16x32_bf16 v[102:105], v[244:247], v[180:183], v[102:105]
	v_mfma_f32_16x16x32_bf16 v[94:97], v[244:247], v[184:187], v[94:97]
	v_mfma_f32_16x16x32_bf16 v[86:89], v[244:247], v[188:191], v[86:89]
	v_mfma_f32_16x16x32_bf16 v[78:81], v[244:247], v[236:239], v[78:81]
	v_mfma_f32_16x16x32_bf16 v[82:85], v[148:151], v[180:183], v[82:85]
	v_mfma_f32_16x16x32_bf16 v[74:77], v[148:151], v[184:187], v[74:77]
	v_mfma_f32_16x16x32_bf16 v[70:73], v[148:151], v[188:191], v[70:73]
	v_mfma_f32_16x16x32_bf16 v[66:69], v[148:151], v[236:239], v[66:69]
	v_mfma_f32_16x16x32_bf16 v[98:101], v[152:155], v[180:183], v[98:101]
	v_mfma_f32_16x16x32_bf16 v[90:93], v[152:155], v[184:187], v[90:93]
	v_mfma_f32_16x16x32_bf16 v[126:129], v[152:155], v[188:191], v[126:129]
	v_mfma_f32_16x16x32_bf16 v[118:121], v[152:155], v[236:239], v[118:121]
	s_cbranch_vccz .LBB0_177

; DEV f32x4 mfma16(bf16x8 a, bf16x8 b, f32x4 c) { return __builtin_amdgcn_mfma_f32_16x16x32_bf16(a, b, c, 0, 0, 0); }
; #define G_LOAD(RA, RB, KT) { _Pragma("unroll") for (int i = 0; i < 4; i++) { \
;       RA[i] = *(const u32x4*)(Ap + (size_t)(i * 32) * lda + (KT) * 64); RB[i] = *(const u32x4*)(Bp + (size_t)(i * 32) * ldb + (KT) * 64); } }
; #define G_STORE(RA, RB) { _Pragma("unroll") for (int i = 0; i < 4; i++) { \
;       *(u32x4*)(As + (lrow + i * 32) * GLD + lcc * 8) = RA[i]; *(u32x4*)(Bs + (lrow + i * 32) * GLD + lcc * 8) = RB[i]; } }
; template <int TI, int TJ, int KS>
; DEV void mfma_lds(const bf16_t* Arows, int lda, const bf16_t* Brows, int ldb, int i0, int j0, f32x4 (&acc)[TI][TJ]) {
;     ...
;   for (int ks = 0; ks < KS; ks++) {
;     bf16x8 af[TI], bfr[TJ];
; #pragma unroll
;     for (int i = 0; i < TI; i++) af[i] = *(const bf16x8*)(Arows + (i0 + i * 16 + l15) * lda + ks * 32 + quad * 8);
; #pragma unroll
;     for (int j = 0; j < TJ; j++) bfr[j] = *(const bf16x8*)(Brows + (j0 + j * 16 + l15) * ldb + ks * 32 + quad * 8);
; #pragma unroll
;     for (int i = 0; i < TI; i++)
; #pragma unroll
;       for (int j = 0; j < TJ; j++) acc[i][j] = mfma16(af[i], bfr[j], acc[i][j]);
; template <class Epi>
; DEV void gemm_tile(const bf16_t* __restrict__ A, int lda, const bf16_t* __restrict__ Bt, int ldb, int K, int m0, int n0,
;                    Epi& epi, char* smem) {
;     ...
;     mfma_lds<4, 4, 2>(Bs, GLD, As, GLD, wn * 64, wm * 64, acc);
;     __syncthreads();
;     G_STORE(ra1, rb1);
;     __syncthreads();
;     if (kt + 3 < nk) G_LOAD(ra1, rb1, kt + 3);
.LBB0_184:
	v_mov_b32_e32 v130, v195
	s_cmp_gt_u32 s12, 12
	v_and_b32_e32 v135, 15, v130
	v_or_b32_e32 v131, v135, v144
	v_and_b32_e32 v148, 48, v130
	v_mul_u32_u24_e32 v130, 0x50, v131
	v_lshl_add_u32 v147, v130, 1, v148
	v_or_b32_e32 v135, v135, v146
	v_mad_u32_u24 v249, v135, s36, v148
	ds_read_b128 v[148:151], v147 offset:20480
	ds_read_b128 v[164:167], v249
	ds_read_b128 v[168:171], v249 offset:2560
	ds_read_b128 v[172:175], v249 offset:5120
	ds_read_b128 v[176:179], v249 offset:7680
	ds_read_b128 v[152:155], v147 offset:23040
	ds_read_b128 v[156:159], v147 offset:25600
	ds_read_b128 v[160:163], v147 offset:28160
	ds_read_b128 v[180:183], v249 offset:64
	ds_read_b128 v[184:187], v249 offset:2624
	ds_read_b128 v[188:191], v249 offset:5184
	ds_read_b128 v[236:239], v249 offset:7744
	ds_read_b128 v[240:243], v147 offset:20544
	ds_read_b128 v[244:247], v147 offset:23104
	s_waitcnt lgkmcnt(12)
	v_mfma_f32_16x16x32_bf16 v[106:109], v[148:151], v[164:167], v[106:109]
	s_waitcnt lgkmcnt(11)
	v_mfma_f32_16x16x32_bf16 v[122:125], v[148:151], v[168:171], v[122:125]
	s_waitcnt lgkmcnt(10)
	v_mfma_f32_16x16x32_bf16 v[114:117], v[148:151], v[172:175], v[114:117]
	s_waitcnt lgkmcnt(9)
	v_mfma_f32_16x16x32_bf16 v[110:113], v[148:151], v[176:179], v[110:113]
	ds_read_b128 v[148:151], v147 offset:25664
	s_waitcnt lgkmcnt(9)
	v_mfma_f32_16x16x32_bf16 v[102:105], v[152:155], v[164:167], v[102:105]
	v_mfma_f32_16x16x32_bf16 v[94:97], v[152:155], v[168:171], v[94:97]
	v_mfma_f32_16x16x32_bf16 v[86:89], v[152:155], v[172:175], v[86:89]
	v_mfma_f32_16x16x32_bf16 v[78:81], v[152:155], v[176:179], v[78:81]
	ds_read_b128 v[152:155], v147 offset:28224
	s_waitcnt lgkmcnt(9)
	v_mfma_f32_16x16x32_bf16 v[82:85], v[156:159], v[164:167], v[82:85]
	v_mfma_f32_16x16x32_bf16 v[74:77], v[156:159], v[168:171], v[74:77]
	v_mfma_f32_16x16x32_bf16 v[70:73], v[156:159], v[172:175], v[70:73]
	v_mfma_f32_16x16x32_bf16 v[66:69], v[156:159], v[176:179], v[66:69]
	s_waitcnt lgkmcnt(8)
	v_mfma_f32_16x16x32_bf16 v[98:101], v[160:163], v[164:167], v[98:101]
	v_mfma_f32_16x16x32_bf16 v[90:93], v[160:163], v[168:171], v[90:93]
	v_mfma_f32_16x16x32_bf16 v[126:129], v[160:163], v[172:175], v[126:129]
	v_mfma_f32_16x16x32_bf16 v[118:121], v[160:163], v[176:179], v[118:121]
	s_waitcnt lgkmcnt(0)
	v_mfma_f32_16x16x32_bf16 v[106:109], v[240:243], v[180:183], v[106:109]
	s_barrier
	v_mfma_f32_16x16x32_bf16 v[122:125], v[240:243], v[184:187], v[122:125]
	s_waitcnt vmcnt(8)
	ds_write_b128 v134, v[6:9]
	v_mfma_f32_16x16x32_bf16 v[114:117], v[240:243], v[188:191], v[114:117]
	ds_write_b128 v134, v[14:17] offset:20480
	v_mfma_f32_16x16x32_bf16 v[110:113], v[240:243], v[236:239], v[110:113]
	ds_write_b128 v134, v[22:25] offset:5120
	v_mfma_f32_16x16x32_bf16 v[102:105], v[244:247], v[180:183], v[102:105]
	ds_write_b128 v134, v[30:33] offset:25600
	v_mfma_f32_16x16x32_bf16 v[94:97], v[244:247], v[184:187], v[94:97]
	ds_write_b128 v134, v[38:41] offset:10240
	v_mfma_f32_16x16x32_bf16 v[86:89], v[244:247], v[188:191], v[86:89]
	ds_write_b128 v134, v[46:49] offset:30720
	v_mfma_f32_16x16x32_bf16 v[78:81], v[244:247], v[236:239], v[78:81]
	ds_write_b128 v134, v[54:57] offset:15360
	v_mfma_f32_16x16x32_bf16 v[82:85], v[148:151], v[180:183], v[82:85]
	ds_write_b128 v134, v[62:65] offset:35840
	v_mfma_f32_16x16x32_bf16 v[74:77], v[148:151], v[184:187], v[74:77]
	v_mfma_f32_16x16x32_bf16 v[70:73], v[148:151], v[188:191], v[70:73]
	s_waitcnt lgkmcnt(0)
	s_barrier
	v_mfma_f32_16x16x32_bf16 v[66:69], v[148:151], v[236:239], v[66:69]
	v_mfma_f32_16x16x32_bf16 v[98:101], v[152:155], v[180:183], v[98:101]
	v_mfma_f32_16x16x32_bf16 v[90:93], v[152:155], v[184:187], v[90:93]
	v_mfma_f32_16x16x32_bf16 v[126:129], v[152:155], v[188:191], v[126:129]
	v_mfma_f32_16x16x32_bf16 v[118:121], v[152:155], v[236:239], v[118:121]
	s_cbranch_scc1 .LBB0_181
	v_add_co_u32_e32 v6, vcc, 0x4200000, v142
	s_nop 1
	v_addc_co_u32_e32 v7, vcc, 0, v143, vcc
	v_add_co_u32_e32 v14, vcc, 0xba00000, v140
	global_load_dwordx4 v[6:9], v[6:7], off offset:384
	s_nop 0
	v_addc_co_u32_e32 v15, vcc, 0, v141, vcc
	v_add_co_u32_e32 v22, vcc, 0x4211000, v142
	global_load_dwordx4 v[14:17], v[14:15], off offset:384
	s_nop 0
	v_addc_co_u32_e32 v23, vcc, 0, v143, vcc
	v_add_co_u32_e32 v30, vcc, 0xba11000, v140
	global_load_dwordx4 v[22:25], v[22:23], off offset:384
	s_nop 0
	v_addc_co_u32_e32 v31, vcc, 0, v141, vcc
	v_add_co_u32_e32 v38, vcc, 0x4222000, v142
	global_load_dwordx4 v[30:33], v[30:31], off offset:384
	s_nop 0
	v_addc_co_u32_e32 v39, vcc, 0, v143, vcc
	v_add_co_u32_e32 v46, vcc, 0xba22000, v140
	global_load_dwordx4 v[38:41], v[38:39], off offset:384
	s_nop 0
	v_addc_co_u32_e32 v47, vcc, 0, v141, vcc
	v_add_co_u32_e32 v54, vcc, 0x4233000, v142
	global_load_dwordx4 v[46:49], v[46:47], off offset:384
	s_nop 0
	v_addc_co_u32_e32 v55, vcc, 0, v143, vcc
	v_add_co_u32_e32 v62, vcc, 0xba33000, v140
	global_load_dwordx4 v[54:57], v[54:55], off offset:384
	s_nop 0
	v_addc_co_u32_e32 v63, vcc, 0, v141, vcc
	global_load_dwordx4 v[62:65], v[62:63], off offset:384
	s_branch .LBB0_181

; DEV f32x4 mfma16(bf16x8 a, bf16x8 b, f32x4 c) { return __builtin_amdgcn_mfma_f32_16x16x32_bf16(a, b, c, 0, 0, 0); }
; #define G_LOAD(RA, RB, KT) { _Pragma("unroll") for (int i = 0; i < 4; i++) { \
;       RA[i] = *(const u32x4*)(Ap + (size_t)(i * 32) * lda + (KT) * 64); RB[i] = *(const u32x4*)(Bp + (size_t)(i * 32) * ldb + (KT) * 64); } }
; template <int TI, int TJ, int KS>
; DEV void mfma_lds(const bf16_t* Arows, int lda, const bf16_t* Brows, int ldb, int i0, int j0, f32x4 (&acc)[TI][TJ]) {
;     ...
;   for (int ks = 0; ks < KS; ks++) {
;     bf16x8 af[TI], bfr[TJ];
; #pragma unroll
;     for (int i = 0; i < TI; i++) af[i] = *(const bf16x8*)(Arows + (i0 + i * 16 + l15) * lda + ks * 32 + quad * 8);
; #pragma unroll
;     for (int j = 0; j < TJ; j++) bfr[j] = *(const bf16x8*)(Brows + (j0 + j * 16 + l15) * ldb + ks * 32 + quad * 8);
; #pragma unroll
;     for (int i = 0; i < TI; i++)
; #pragma unroll
;       for (int j = 0; j < TJ; j++) acc[i][j] = mfma16(af[i], bfr[j], acc[i][j]);
; template <class Epi>
; DEV void gemm_tile(const bf16_t* __restrict__ A, int lda, const bf16_t* __restrict__ Bt, int ldb, int K, int m0, int n0,
;                    Epi& epi, char* smem) {
;     ...
;     if (kt + 3 < nk) G_LOAD(ra1, rb1, kt + 3);
;     mfma_lds<4, 4, 2>(Bs, GLD, As, GLD, wn * 64, wm * 64, acc);
.LBB0_200:
	v_mov_b32_e32 v131, v195
	v_and_b32_e32 v143, 15, v131
	v_or_b32_e32 v144, v143, v140
	v_and_b32_e32 v148, 48, v131
	v_mul_u32_u24_e32 v131, 0x50, v144
	v_lshl_add_u32 v131, v131, 1, v148
	v_or_b32_e32 v143, v143, v142
	v_mad_u32_u24 v249, v143, s36, v148
	v_lshl_add_u64 v[132:133], v[132:133], 0, s[34:35]
	v_lshl_add_u64 v[134:135], v[134:135], 0, s[34:35]
	s_and_b64 vcc, exec, s[16:17]
	ds_read_b128 v[144:147], v131 offset:20480
	ds_read_b128 v[160:163], v249
	ds_read_b128 v[164:167], v249 offset:2560
	ds_read_b128 v[168:171], v249 offset:5120
	ds_read_b128 v[172:175], v249 offset:7680
	ds_read_b128 v[148:151], v131 offset:23040
	ds_read_b128 v[152:155], v131 offset:25600
	ds_read_b128 v[156:159], v131 offset:28160
	ds_read_b128 v[176:179], v249 offset:64
	ds_read_b128 v[180:183], v249 offset:2624
	ds_read_b128 v[188:191], v249 offset:5184
	ds_read_b128 v[236:239], v249 offset:7744
	ds_read_b128 v[240:243], v131 offset:20544
	ds_read_b128 v[244:247], v131 offset:23104
	s_waitcnt lgkmcnt(12)
	v_mfma_f32_16x16x32_bf16 v[126:129], v[144:147], v[160:163], v[126:129]
	s_waitcnt lgkmcnt(11)
	v_mfma_f32_16x16x32_bf16 v[122:125], v[144:147], v[164:167], v[122:125]
	s_waitcnt lgkmcnt(10)
	v_mfma_f32_16x16x32_bf16 v[118:121], v[144:147], v[168:171], v[118:121]
	s_waitcnt lgkmcnt(9)
	v_mfma_f32_16x16x32_bf16 v[114:117], v[144:147], v[172:175], v[114:117]
	ds_read_b128 v[144:147], v131 offset:25664
	s_waitcnt lgkmcnt(9)
	v_mfma_f32_16x16x32_bf16 v[110:113], v[148:151], v[160:163], v[110:113]
	v_mfma_f32_16x16x32_bf16 v[74:77], v[148:151], v[164:167], v[74:77]
	v_mfma_f32_16x16x32_bf16 v[38:41], v[148:151], v[168:171], v[38:41]
	v_mfma_f32_16x16x32_bf16 v[34:37], v[148:151], v[172:175], v[34:37]
	ds_read_b128 v[148:151], v131 offset:28224
	s_waitcnt lgkmcnt(9)
	v_mfma_f32_16x16x32_bf16 v[30:33], v[152:155], v[160:163], v[30:33]
	v_mfma_f32_16x16x32_bf16 v[26:29], v[152:155], v[164:167], v[26:29]
	v_mfma_f32_16x16x32_bf16 v[22:25], v[152:155], v[168:171], v[22:25]
	v_mfma_f32_16x16x32_bf16 v[18:21], v[152:155], v[172:175], v[18:21]
	s_waitcnt lgkmcnt(8)
	v_mfma_f32_16x16x32_bf16 v[14:17], v[156:159], v[160:163], v[14:17]
	v_mfma_f32_16x16x32_bf16 v[10:13], v[156:159], v[164:167], v[10:13]
	v_mfma_f32_16x16x32_bf16 v[6:9], v[156:159], v[168:171], v[6:9]
	v_mfma_f32_16x16x32_bf16 v[2:5], v[156:159], v[172:175], v[2:5]
	s_waitcnt lgkmcnt(0)
	v_mfma_f32_16x16x32_bf16 v[126:129], v[240:243], v[176:179], v[126:129]
	v_mfma_f32_16x16x32_bf16 v[122:125], v[240:243], v[180:183], v[122:125]
	v_mfma_f32_16x16x32_bf16 v[118:121], v[240:243], v[188:191], v[118:121]
	v_mfma_f32_16x16x32_bf16 v[114:117], v[240:243], v[236:239], v[114:117]
	v_mfma_f32_16x16x32_bf16 v[110:113], v[244:247], v[176:179], v[110:113]
	v_mfma_f32_16x16x32_bf16 v[74:77], v[244:247], v[180:183], v[74:77]
	v_mfma_f32_16x16x32_bf16 v[38:41], v[244:247], v[188:191], v[38:41]
	v_mfma_f32_16x16x32_bf16 v[34:37], v[244:247], v[236:239], v[34:37]
	v_mfma_f32_16x16x32_bf16 v[30:33], v[144:147], v[176:179], v[30:33]
	v_mfma_f32_16x16x32_bf16 v[26:29], v[144:147], v[180:183], v[26:29]
	v_mfma_f32_16x16x32_bf16 v[22:25], v[144:147], v[188:191], v[22:25]
	v_mfma_f32_16x16x32_bf16 v[18:21], v[144:147], v[236:239], v[18:21]
	v_mfma_f32_16x16x32_bf16 v[14:17], v[148:151], v[176:179], v[14:17]
	v_mfma_f32_16x16x32_bf16 v[10:13], v[148:151], v[180:183], v[10:13]
	v_mfma_f32_16x16x32_bf16 v[6:9], v[148:151], v[188:191], v[6:9]
	v_mfma_f32_16x16x32_bf16 v[2:5], v[148:151], v[236:239], v[2:5]
	s_cbranch_vccnz .LBB0_205

; DEV f32x4 mfma16(bf16x8 a, bf16x8 b, f32x4 c) { return __builtin_amdgcn_mfma_f32_16x16x32_bf16(a, b, c, 0, 0, 0); }
; #define G_LOAD(RA, RB, KT) { _Pragma("unroll") for (int i = 0; i < 4; i++) { \
;       RA[i] = *(const u32x4*)(Ap + (size_t)(i * 32) * lda + (KT) * 64); RB[i] = *(const u32x4*)(Bp + (size_t)(i * 32) * ldb + (KT) * 64); } }
; #define G_STORE(RA, RB) { _Pragma("unroll") for (int i = 0; i < 4; i++) { \
;       *(u32x4*)(As + (lrow + i * 32) * GLD + lcc * 8) = RA[i]; *(u32x4*)(Bs + (lrow + i * 32) * GLD + lcc * 8) = RB[i]; } }
; template <int TI, int TJ, int KS>
; DEV void mfma_lds(const bf16_t* Arows, int lda, const bf16_t* Brows, int ldb, int i0, int j0, f32x4 (&acc)[TI][TJ]) {
;     ...
;   for (int ks = 0; ks < KS; ks++) {
;     bf16x8 af[TI], bfr[TJ];
; #pragma unroll
;     for (int i = 0; i < TI; i++) af[i] = *(const bf16x8*)(Arows + (i0 + i * 16 + l15) * lda + ks * 32 + quad * 8);
; #pragma unroll
;     for (int j = 0; j < TJ; j++) bfr[j] = *(const bf16x8*)(Brows + (j0 + j * 16 + l15) * ldb + ks * 32 + quad * 8);
; #pragma unroll
;     for (int i = 0; i < TI; i++)
; #pragma unroll
;       for (int j = 0; j < TJ; j++) acc[i][j] = mfma16(af[i], bfr[j], acc[i][j]);
; template <class Epi>
; DEV void gemm_tile(const bf16_t* __restrict__ A, int lda, const bf16_t* __restrict__ Bt, int ldb, int K, int m0, int n0,
;                    Epi& epi, char* smem) {
;     ...
;   for (int kt = 0; kt < nk; kt += 2) {
;     __syncthreads();
;     G_STORE(ra0, rb0);
;     __syncthreads();
;     if (kt + 2 < nk) G_LOAD(ra0, rb0, kt + 2);
;     mfma_lds<4, 4, 2>(Bs, GLD, As, GLD, wn * 64, wm * 64, acc);
;     __syncthreads();
;     G_STORE(ra1, rb1);
;     __syncthreads();
;     if (kt + 3 < nk) G_LOAD(ra1, rb1, kt + 3);
;     mfma_lds<4, 4, 2>(Bs, GLD, As, GLD, wn * 64, wm * 64, acc);
;   }
.LBB0_203:
	v_mov_b32_e32 v131, v195
	s_cmp_gt_u32 s1, 12
	v_and_b32_e32 v143, 15, v131
	v_or_b32_e32 v144, v143, v140
	v_and_b32_e32 v148, 48, v131
	v_mul_u32_u24_e32 v131, 0x50, v144
	v_lshl_add_u32 v131, v131, 1, v148
	v_or_b32_e32 v143, v143, v142
	v_mad_u32_u24 v249, v143, s36, v148
	ds_read_b128 v[144:147], v131 offset:20480
	ds_read_b128 v[160:163], v249
	ds_read_b128 v[164:167], v249 offset:2560
	ds_read_b128 v[168:171], v249 offset:5120
	ds_read_b128 v[172:175], v249 offset:7680
	ds_read_b128 v[148:151], v131 offset:23040
	ds_read_b128 v[152:155], v131 offset:25600
	ds_read_b128 v[156:159], v131 offset:28160
	ds_read_b128 v[176:179], v249 offset:64
	ds_read_b128 v[180:183], v249 offset:2624
	ds_read_b128 v[188:191], v249 offset:5184
	ds_read_b128 v[236:239], v249 offset:7744
	ds_read_b128 v[240:243], v131 offset:20544
	ds_read_b128 v[244:247], v131 offset:23104
	s_waitcnt lgkmcnt(12)
	v_mfma_f32_16x16x32_bf16 v[126:129], v[144:147], v[160:163], v[126:129]
	s_waitcnt lgkmcnt(11)
	v_mfma_f32_16x16x32_bf16 v[122:125], v[144:147], v[164:167], v[122:125]
	s_waitcnt lgkmcnt(10)
	v_mfma_f32_16x16x32_bf16 v[118:121], v[144:147], v[168:171], v[118:121]
	s_waitcnt lgkmcnt(9)
	v_mfma_f32_16x16x32_bf16 v[114:117], v[144:147], v[172:175], v[114:117]
	ds_read_b128 v[144:147], v131 offset:25664
	s_waitcnt lgkmcnt(9)
	v_mfma_f32_16x16x32_bf16 v[110:113], v[148:151], v[160:163], v[110:113]
	v_mfma_f32_16x16x32_bf16 v[74:77], v[148:151], v[164:167], v[74:77]
	v_mfma_f32_16x16x32_bf16 v[38:41], v[148:151], v[168:171], v[38:41]
	v_mfma_f32_16x16x32_bf16 v[34:37], v[148:151], v[172:175], v[34:37]
	ds_read_b128 v[148:151], v131 offset:28224
	s_waitcnt lgkmcnt(9)
	v_mfma_f32_16x16x32_bf16 v[30:33], v[152:155], v[160:163], v[30:33]
	v_mfma_f32_16x16x32_bf16 v[26:29], v[152:155], v[164:167], v[26:29]
	v_mfma_f32_16x16x32_bf16 v[22:25], v[152:155], v[168:171], v[22:25]
	v_mfma_f32_16x16x32_bf16 v[18:21], v[152:155], v[172:175], v[18:21]
	s_waitcnt lgkmcnt(8)
	v_mfma_f32_16x16x32_bf16 v[14:17], v[156:159], v[160:163], v[14:17]
	v_mfma_f32_16x16x32_bf16 v[10:13], v[156:159], v[164:167], v[10:13]
	v_mfma_f32_16x16x32_bf16 v[6:9], v[156:159], v[168:171], v[6:9]
	v_mfma_f32_16x16x32_bf16 v[2:5], v[156:159], v[172:175], v[2:5]
	s_waitcnt lgkmcnt(0)
	v_mfma_f32_16x16x32_bf16 v[126:129], v[240:243], v[176:179], v[126:129]
	s_barrier
	v_mfma_f32_16x16x32_bf16 v[122:125], v[240:243], v[180:183], v[122:125]
	s_waitcnt vmcnt(8)
	ds_write_b128 v130, v[46:49]
	v_mfma_f32_16x16x32_bf16 v[118:121], v[240:243], v[188:191], v[118:121]
	ds_write_b128 v130, v[54:57] offset:20480
	v_mfma_f32_16x16x32_bf16 v[114:117], v[240:243], v[236:239], v[114:117]
	ds_write_b128 v130, v[62:65] offset:5120
	v_mfma_f32_16x16x32_bf16 v[110:113], v[244:247], v[176:179], v[110:113]
	ds_write_b128 v130, v[70:73] offset:25600
	v_mfma_f32_16x16x32_bf16 v[74:77], v[244:247], v[180:183], v[74:77]
	ds_write_b128 v130, v[82:85] offset:10240
	v_mfma_f32_16x16x32_bf16 v[38:41], v[244:247], v[188:191], v[38:41]
	ds_write_b128 v130, v[90:93] offset:30720
	v_mfma_f32_16x16x32_bf16 v[34:37], v[244:247], v[236:239], v[34:37]
	ds_write_b128 v130, v[98:101] offset:15360
	v_mfma_f32_16x16x32_bf16 v[30:33], v[144:147], v[176:179], v[30:33]
	ds_write_b128 v130, v[106:109] offset:35840
	v_mfma_f32_16x16x32_bf16 v[26:29], v[144:147], v[180:183], v[26:29]
	v_mfma_f32_16x16x32_bf16 v[22:25], v[144:147], v[188:191], v[22:25]
	s_waitcnt lgkmcnt(0)
	s_barrier
	v_mfma_f32_16x16x32_bf16 v[18:21], v[144:147], v[236:239], v[18:21]
	v_mfma_f32_16x16x32_bf16 v[14:17], v[148:151], v[176:179], v[14:17]
	v_mfma_f32_16x16x32_bf16 v[10:13], v[148:151], v[180:183], v[10:13]
	v_mfma_f32_16x16x32_bf16 v[6:9], v[148:151], v[188:191], v[6:9]
	v_mfma_f32_16x16x32_bf16 v[2:5], v[148:151], v[236:239], v[2:5]
	s_cbranch_scc1 .LBB0_200
	v_add_co_u32_e32 v46, vcc, 0x4200000, v138
	s_nop 1
	v_addc_co_u32_e32 v47, vcc, 0, v139, vcc
	v_add_co_u32_e32 v54, vcc, 0xb3a0000, v136
	global_load_dwordx4 v[46:49], v[46:47], off offset:384
	s_nop 0
	v_addc_co_u32_e32 v55, vcc, 0, v137, vcc
	v_add_co_u32_e32 v62, vcc, 0x4211000, v138
	global_load_dwordx4 v[54:57], v[54:55], off offset:384
	s_nop 0
	v_addc_co_u32_e32 v63, vcc, 0, v139, vcc
	v_add_co_u32_e32 v70, vcc, 0xb3b1000, v136
	global_load_dwordx4 v[62:65], v[62:63], off offset:384
	s_nop 0
	v_addc_co_u32_e32 v71, vcc, 0, v137, vcc
	v_add_co_u32_e32 v82, vcc, 0x4222000, v138
	global_load_dwordx4 v[70:73], v[70:71], off offset:384
	s_nop 0
	v_addc_co_u32_e32 v83, vcc, 0, v139, vcc
	v_add_co_u32_e32 v90, vcc, 0xb3c2000, v136
	global_load_dwordx4 v[82:85], v[82:83], off offset:384
	s_nop 0
	v_addc_co_u32_e32 v91, vcc, 0, v137, vcc
	v_add_co_u32_e32 v98, vcc, 0x4233000, v138
	global_load_dwordx4 v[90:93], v[90:91], off offset:384
	s_nop 0
	v_addc_co_u32_e32 v99, vcc, 0, v139, vcc
	v_add_co_u32_e32 v106, vcc, 0xb3d3000, v136
	global_load_dwordx4 v[98:101], v[98:99], off offset:384
	s_nop 0
	v_addc_co_u32_e32 v107, vcc, 0, v137, vcc
	global_load_dwordx4 v[106:109], v[106:107], off offset:384
	s_branch .LBB0_200

; DEV f32x4 mfma16(bf16x8 a, bf16x8 b, f32x4 c) { return __builtin_amdgcn_mfma_f32_16x16x32_bf16(a, b, c, 0, 0, 0); }
; #define G_LOAD(RA, RB, KT) { _Pragma("unroll") for (int i = 0; i < 4; i++) { \
;       RA[i] = *(const u32x4*)(Ap + (size_t)(i * 32) * lda + (KT) * 64); RB[i] = *(const u32x4*)(Bp + (size_t)(i * 32) * ldb + (KT) * 64); } }
; #define G_STORE(RA, RB) { _Pragma("unroll") for (int i = 0; i < 4; i++) { \
;       *(u32x4*)(As + (lrow + i * 32) * GLD + lcc * 8) = RA[i]; *(u32x4*)(Bs + (lrow + i * 32) * GLD + lcc * 8) = RB[i]; } }
; template <int TI, int TJ, int KS>
; DEV void mfma_lds(const bf16_t* Arows, int lda, const bf16_t* Brows, int ldb, int i0, int j0, f32x4 (&acc)[TI][TJ]) {
;     ...
;   for (int ks = 0; ks < KS; ks++) {
;     bf16x8 af[TI], bfr[TJ];
; #pragma unroll
;     for (int i = 0; i < TI; i++) af[i] = *(const bf16x8*)(Arows + (i0 + i * 16 + l15) * lda + ks * 32 + quad * 8);
; #pragma unroll
;     for (int j = 0; j < TJ; j++) bfr[j] = *(const bf16x8*)(Brows + (j0 + j * 16 + l15) * ldb + ks * 32 + quad * 8);
; #pragma unroll
;     for (int i = 0; i < TI; i++)
; #pragma unroll
;       for (int j = 0; j < TJ; j++) acc[i][j] = mfma16(af[i], bfr[j], acc[i][j]);
; template <class Epi>
; DEV void gemm_tile(const bf16_t* __restrict__ A, int lda, const bf16_t* __restrict__ Bt, int ldb, int K, int m0, int n0,
;                    Epi& epi, char* smem) {
;     ...
;   for (int kt = 0; kt < nk; kt += 2) {
;     __syncthreads();
;     G_STORE(ra0, rb0);
;     __syncthreads();
;     if (kt + 2 < nk) G_LOAD(ra0, rb0, kt + 2);
;     mfma_lds<4, 4, 2>(Bs, GLD, As, GLD, wn * 64, wm * 64, acc);
;     __syncthreads();
;     G_STORE(ra1, rb1);
;     __syncthreads();
;     if (kt + 3 < nk) G_LOAD(ra1, rb1, kt + 3);
;     mfma_lds<4, 4, 2>(Bs, GLD, As, GLD, wn * 64, wm * 64, acc);
;   }
.LBB0_646:
	v_mov_b32_e32 v130, v195
	v_and_b32_e32 v135, 15, v130
	v_or_b32_e32 v131, v135, v144
	v_and_b32_e32 v148, 48, v130
	v_mul_u32_u24_e32 v130, 0x50, v131
	v_lshl_add_u32 v147, v130, 1, v148
	v_or_b32_e32 v135, v135, v146
	v_mad_u32_u24 v249, v135, s36, v148
	v_lshl_add_u64 v[136:137], v[136:137], 0, s[34:35]
	v_lshl_add_u64 v[138:139], v[138:139], 0, s[34:35]
	s_andn2_b64 vcc, exec, s[8:9]
	ds_read_b128 v[148:151], v147 offset:20480
	ds_read_b128 v[164:167], v249
	ds_read_b128 v[168:171], v249 offset:2560
	ds_read_b128 v[172:175], v249 offset:5120
	ds_read_b128 v[176:179], v249 offset:7680
	ds_read_b128 v[152:155], v147 offset:23040
	ds_read_b128 v[156:159], v147 offset:25600
	ds_read_b128 v[160:163], v147 offset:28160
	ds_read_b128 v[180:183], v249 offset:64
	ds_read_b128 v[184:187], v249 offset:2624
	ds_read_b128 v[188:191], v249 offset:5184
	ds_read_b128 v[236:239], v249 offset:7744
	ds_read_b128 v[240:243], v147 offset:20544
	ds_read_b128 v[244:247], v147 offset:23104
	s_waitcnt lgkmcnt(12)
	v_mfma_f32_16x16x32_bf16 v[106:109], v[148:151], v[164:167], v[106:109]
	s_waitcnt lgkmcnt(11)
	v_mfma_f32_16x16x32_bf16 v[122:125], v[148:151], v[168:171], v[122:125]
	s_waitcnt lgkmcnt(10)
	v_mfma_f32_16x16x32_bf16 v[114:117], v[148:151], v[172:175], v[114:117]
	s_waitcnt lgkmcnt(9)
	v_mfma_f32_16x16x32_bf16 v[110:113], v[148:151], v[176:179], v[110:113]
	ds_read_b128 v[148:151], v147 offset:25664
	s_waitcnt lgkmcnt(9)
	v_mfma_f32_16x16x32_bf16 v[102:105], v[152:155], v[164:167], v[102:105]
	v_mfma_f32_16x16x32_bf16 v[94:97], v[152:155], v[168:171], v[94:97]
	v_mfma_f32_16x16x32_bf16 v[86:89], v[152:155], v[172:175], v[86:89]
	v_mfma_f32_16x16x32_bf16 v[78:81], v[152:155], v[176:179], v[78:81]
	ds_read_b128 v[152:155], v147 offset:28224
	s_waitcnt lgkmcnt(9)
	v_mfma_f32_16x16x32_bf16 v[82:85], v[156:159], v[164:167], v[82:85]
	v_mfma_f32_16x16x32_bf16 v[74:77], v[156:159], v[168:171], v[74:77]
	v_mfma_f32_16x16x32_bf16 v[70:73], v[156:159], v[172:175], v[70:73]
	v_mfma_f32_16x16x32_bf16 v[66:69], v[156:159], v[176:179], v[66:69]
	s_waitcnt lgkmcnt(8)
	v_mfma_f32_16x16x32_bf16 v[98:101], v[160:163], v[164:167], v[98:101]
	v_mfma_f32_16x16x32_bf16 v[90:93], v[160:163], v[168:171], v[90:93]
	v_mfma_f32_16x16x32_bf16 v[126:129], v[160:163], v[172:175], v[126:129]
	v_mfma_f32_16x16x32_bf16 v[118:121], v[160:163], v[176:179], v[118:121]
	s_waitcnt lgkmcnt(0)
	v_mfma_f32_16x16x32_bf16 v[106:109], v[240:243], v[180:183], v[106:109]
	v_mfma_f32_16x16x32_bf16 v[122:125], v[240:243], v[184:187], v[122:125]
	v_mfma_f32_16x16x32_bf16 v[114:117], v[240:243], v[188:191], v[114:117]
	v_mfma_f32_16x16x32_bf16 v[110:113], v[240:243], v[236:239], v[110:113]
	v_mfma_f32_16x16x32_bf16 v[102:105], v[244:247], v[180:183], v[102:105]
	v_mfma_f32_16x16x32_bf16 v[94:97], v[244:247], v[184:187], v[94:97]
	v_mfma_f32_16x16x32_bf16 v[86:89], v[244:247], v[188:191], v[86:89]
	v_mfma_f32_16x16x32_bf16 v[78:81], v[244:247], v[236:239], v[78:81]
	v_mfma_f32_16x16x32_bf16 v[82:85], v[148:151], v[180:183], v[82:85]
	v_mfma_f32_16x16x32_bf16 v[74:77], v[148:151], v[184:187], v[74:77]
	v_mfma_f32_16x16x32_bf16 v[70:73], v[148:151], v[188:191], v[70:73]
	v_mfma_f32_16x16x32_bf16 v[66:69], v[148:151], v[236:239], v[66:69]
	v_mfma_f32_16x16x32_bf16 v[98:101], v[152:155], v[180:183], v[98:101]
	v_mfma_f32_16x16x32_bf16 v[90:93], v[152:155], v[184:187], v[90:93]
	v_mfma_f32_16x16x32_bf16 v[126:129], v[152:155], v[188:191], v[126:129]
	v_mfma_f32_16x16x32_bf16 v[118:121], v[152:155], v[236:239], v[118:121]
	s_cbranch_vccz .LBB0_642

; DEV f32x4 mfma16(bf16x8 a, bf16x8 b, f32x4 c) { return __builtin_amdgcn_mfma_f32_16x16x32_bf16(a, b, c, 0, 0, 0); }
; #define G_LOAD(RA, RB, KT) { _Pragma("unroll") for (int i = 0; i < 4; i++) { \
;       RA[i] = *(const u32x4*)(Ap + (size_t)(i * 32) * lda + (KT) * 64); RB[i] = *(const u32x4*)(Bp + (size_t)(i * 32) * ldb + (KT) * 64); } }
; #define G_STORE(RA, RB) { _Pragma("unroll") for (int i = 0; i < 4; i++) { \
;       *(u32x4*)(As + (lrow + i * 32) * GLD + lcc * 8) = RA[i]; *(u32x4*)(Bs + (lrow + i * 32) * GLD + lcc * 8) = RB[i]; } }
; template <int TI, int TJ, int KS>
; DEV void mfma_lds(const bf16_t* Arows, int lda, const bf16_t* Brows, int ldb, int i0, int j0, f32x4 (&acc)[TI][TJ]) {
;     ...
;   for (int ks = 0; ks < KS; ks++) {
;     bf16x8 af[TI], bfr[TJ];
; #pragma unroll
;     for (int i = 0; i < TI; i++) af[i] = *(const bf16x8*)(Arows + (i0 + i * 16 + l15) * lda + ks * 32 + quad * 8);
; #pragma unroll
;     for (int j = 0; j < TJ; j++) bfr[j] = *(const bf16x8*)(Brows + (j0 + j * 16 + l15) * ldb + ks * 32 + quad * 8);
; #pragma unroll
;     for (int i = 0; i < TI; i++)
; #pragma unroll
;       for (int j = 0; j < TJ; j++) acc[i][j] = mfma16(af[i], bfr[j], acc[i][j]);
; template <class Epi>
; DEV void gemm_tile(const bf16_t* __restrict__ A, int lda, const bf16_t* __restrict__ Bt, int ldb, int K, int m0, int n0,
;                    Epi& epi, char* smem) {
;     ...
;   for (int kt = 0; kt < nk; kt += 2) {
;     __syncthreads();
;     G_STORE(ra0, rb0);
;     __syncthreads();
;     if (kt + 2 < nk) G_LOAD(ra0, rb0, kt + 2);
;     mfma_lds<4, 4, 2>(Bs, GLD, As, GLD, wn * 64, wm * 64, acc);
;     __syncthreads();
;     G_STORE(ra1, rb1);
;     __syncthreads();
;     if (kt + 3 < nk) G_LOAD(ra1, rb1, kt + 3);
;     mfma_lds<4, 4, 2>(Bs, GLD, As, GLD, wn * 64, wm * 64, acc);
;   }
.LBB0_649:
	v_mov_b32_e32 v130, v195
	s_cmp_gt_u32 s14, 12
	v_and_b32_e32 v135, 15, v130
	v_or_b32_e32 v131, v135, v144
	v_and_b32_e32 v148, 48, v130
	v_mul_u32_u24_e32 v130, 0x50, v131
	v_lshl_add_u32 v147, v130, 1, v148
	v_or_b32_e32 v135, v135, v146
	v_mad_u32_u24 v249, v135, s36, v148
	ds_read_b128 v[148:151], v147 offset:20480
	ds_read_b128 v[164:167], v249
	ds_read_b128 v[168:171], v249 offset:2560
	ds_read_b128 v[172:175], v249 offset:5120
	ds_read_b128 v[176:179], v249 offset:7680
	ds_read_b128 v[152:155], v147 offset:23040
	ds_read_b128 v[156:159], v147 offset:25600
	ds_read_b128 v[160:163], v147 offset:28160
	ds_read_b128 v[180:183], v249 offset:64
	ds_read_b128 v[184:187], v249 offset:2624
	ds_read_b128 v[188:191], v249 offset:5184
	ds_read_b128 v[236:239], v249 offset:7744
	ds_read_b128 v[240:243], v147 offset:20544
	ds_read_b128 v[244:247], v147 offset:23104
	s_waitcnt lgkmcnt(12)
	v_mfma_f32_16x16x32_bf16 v[106:109], v[148:151], v[164:167], v[106:109]
	s_waitcnt lgkmcnt(11)
	v_mfma_f32_16x16x32_bf16 v[122:125], v[148:151], v[168:171], v[122:125]
	s_waitcnt lgkmcnt(10)
	v_mfma_f32_16x16x32_bf16 v[114:117], v[148:151], v[172:175], v[114:117]
	s_waitcnt lgkmcnt(9)
	v_mfma_f32_16x16x32_bf16 v[110:113], v[148:151], v[176:179], v[110:113]
	ds_read_b128 v[148:151], v147 offset:25664
	s_waitcnt lgkmcnt(9)
	v_mfma_f32_16x16x32_bf16 v[102:105], v[152:155], v[164:167], v[102:105]
	v_mfma_f32_16x16x32_bf16 v[94:97], v[152:155], v[168:171], v[94:97]
	v_mfma_f32_16x16x32_bf16 v[86:89], v[152:155], v[172:175], v[86:89]
	v_mfma_f32_16x16x32_bf16 v[78:81], v[152:155], v[176:179], v[78:81]
	ds_read_b128 v[152:155], v147 offset:28224
	s_waitcnt lgkmcnt(9)
	v_mfma_f32_16x16x32_bf16 v[82:85], v[156:159], v[164:167], v[82:85]
	v_mfma_f32_16x16x32_bf16 v[74:77], v[156:159], v[168:171], v[74:77]
	v_mfma_f32_16x16x32_bf16 v[70:73], v[156:159], v[172:175], v[70:73]
	v_mfma_f32_16x16x32_bf16 v[66:69], v[156:159], v[176:179], v[66:69]
	s_waitcnt lgkmcnt(8)
	v_mfma_f32_16x16x32_bf16 v[98:101], v[160:163], v[164:167], v[98:101]
	v_mfma_f32_16x16x32_bf16 v[90:93], v[160:163], v[168:171], v[90:93]
	v_mfma_f32_16x16x32_bf16 v[126:129], v[160:163], v[172:175], v[126:129]
	v_mfma_f32_16x16x32_bf16 v[118:121], v[160:163], v[176:179], v[118:121]
	s_waitcnt lgkmcnt(0)
	v_mfma_f32_16x16x32_bf16 v[106:109], v[240:243], v[180:183], v[106:109]
	s_barrier
	v_mfma_f32_16x16x32_bf16 v[122:125], v[240:243], v[184:187], v[122:125]
	s_waitcnt vmcnt(8)
	ds_write_b128 v134, v[6:9]
	v_mfma_f32_16x16x32_bf16 v[114:117], v[240:243], v[188:191], v[114:117]
	ds_write_b128 v134, v[14:17] offset:20480
	v_mfma_f32_16x16x32_bf16 v[110:113], v[240:243], v[236:239], v[110:113]
	ds_write_b128 v134, v[22:25] offset:5120
	v_mfma_f32_16x16x32_bf16 v[102:105], v[244:247], v[180:183], v[102:105]
	ds_write_b128 v134, v[30:33] offset:25600
	v_mfma_f32_16x16x32_bf16 v[94:97], v[244:247], v[184:187], v[94:97]
	ds_write_b128 v134, v[38:41] offset:10240
	v_mfma_f32_16x16x32_bf16 v[86:89], v[244:247], v[188:191], v[86:89]
	ds_write_b128 v134, v[46:49] offset:30720
	v_mfma_f32_16x16x32_bf16 v[78:81], v[244:247], v[236:239], v[78:81]
	ds_write_b128 v134, v[54:57] offset:15360
	v_mfma_f32_16x16x32_bf16 v[82:85], v[148:151], v[180:183], v[82:85]
	ds_write_b128 v134, v[62:65] offset:35840
	v_mfma_f32_16x16x32_bf16 v[74:77], v[148:151], v[184:187], v[74:77]
	v_mfma_f32_16x16x32_bf16 v[70:73], v[148:151], v[188:191], v[70:73]
	s_waitcnt lgkmcnt(0)
	s_barrier
	v_mfma_f32_16x16x32_bf16 v[66:69], v[148:151], v[236:239], v[66:69]
	v_mfma_f32_16x16x32_bf16 v[98:101], v[152:155], v[180:183], v[98:101]
	v_mfma_f32_16x16x32_bf16 v[90:93], v[152:155], v[184:187], v[90:93]
	v_mfma_f32_16x16x32_bf16 v[126:129], v[152:155], v[188:191], v[126:129]
	v_mfma_f32_16x16x32_bf16 v[118:121], v[152:155], v[236:239], v[118:121]
	s_cbranch_scc1 .LBB0_646
	v_add_co_u32_e32 v6, vcc, 0x4200000, v142
	s_nop 1
	v_addc_co_u32_e32 v7, vcc, 0, v143, vcc
	v_add_co_u32_e32 v14, vcc, 0xb5c0000, v140
	global_load_dwordx4 v[6:9], v[6:7], off offset:384
	s_nop 0
	v_addc_co_u32_e32 v15, vcc, 0, v141, vcc
	v_add_co_u32_e32 v22, vcc, 0x4211000, v142
	global_load_dwordx4 v[14:17], v[14:15], off offset:384
	s_nop 0
	v_addc_co_u32_e32 v23, vcc, 0, v143, vcc
	v_add_co_u32_e32 v30, vcc, 0xb5d1000, v140
	global_load_dwordx4 v[22:25], v[22:23], off offset:384
	s_nop 0
	v_addc_co_u32_e32 v31, vcc, 0, v141, vcc
	v_add_co_u32_e32 v38, vcc, 0x4222000, v142
	global_load_dwordx4 v[30:33], v[30:31], off offset:384
	s_nop 0
	v_addc_co_u32_e32 v39, vcc, 0, v143, vcc
	v_add_co_u32_e32 v46, vcc, 0xb5e2000, v140
	global_load_dwordx4 v[38:41], v[38:39], off offset:384
	s_nop 0
	v_addc_co_u32_e32 v47, vcc, 0, v141, vcc
	v_add_co_u32_e32 v54, vcc, 0x4233000, v142
	global_load_dwordx4 v[46:49], v[46:47], off offset:384
	s_nop 0
	v_addc_co_u32_e32 v55, vcc, 0, v143, vcc
	v_add_co_u32_e32 v62, vcc, 0xb5f3000, v140
	global_load_dwordx4 v[54:57], v[54:55], off offset:384
	s_nop 0
	v_addc_co_u32_e32 v63, vcc, 0, v141, vcc
	global_load_dwordx4 v[62:65], v[62:63], off offset:384
	s_branch .LBB0_646

; DEV f32x4 mfma16(bf16x8 a, bf16x8 b, f32x4 c) { return __builtin_amdgcn_mfma_f32_16x16x32_bf16(a, b, c, 0, 0, 0); }
; #define G_LOAD(RA, RB, KT) { _Pragma("unroll") for (int i = 0; i < 4; i++) { \
;       RA[i] = *(const u32x4*)(Ap + (size_t)(i * 32) * lda + (KT) * 64); RB[i] = *(const u32x4*)(Bp + (size_t)(i * 32) * ldb + (KT) * 64); } }
; #define G_STORE(RA, RB) { _Pragma("unroll") for (int i = 0; i < 4; i++) { \
;       *(u32x4*)(As + (lrow + i * 32) * GLD + lcc * 8) = RA[i]; *(u32x4*)(Bs + (lrow + i * 32) * GLD + lcc * 8) = RB[i]; } }
; template <int TI, int TJ, int KS>
; DEV void mfma_lds(const bf16_t* Arows, int lda, const bf16_t* Brows, int ldb, int i0, int j0, f32x4 (&acc)[TI][TJ]) {
;     ...
;   for (int ks = 0; ks < KS; ks++) {
;     bf16x8 af[TI], bfr[TJ];
; #pragma unroll
;     for (int i = 0; i < TI; i++) af[i] = *(const bf16x8*)(Arows + (i0 + i * 16 + l15) * lda + ks * 32 + quad * 8);
; #pragma unroll
;     for (int j = 0; j < TJ; j++) bfr[j] = *(const bf16x8*)(Brows + (j0 + j * 16 + l15) * ldb + ks * 32 + quad * 8);
; #pragma unroll
;     for (int i = 0; i < TI; i++)
; #pragma unroll
;       for (int j = 0; j < TJ; j++) acc[i][j] = mfma16(af[i], bfr[j], acc[i][j]);
; template <class Epi>
; DEV void gemm_tile(const bf16_t* __restrict__ A, int lda, const bf16_t* __restrict__ Bt, int ldb, int K, int m0, int n0,
;                    Epi& epi, char* smem) {
;     ...
;   for (int kt = 0; kt < nk; kt += 2) {
;     __syncthreads();
;     G_STORE(ra0, rb0);
;     __syncthreads();
;     if (kt + 2 < nk) G_LOAD(ra0, rb0, kt + 2);
;     mfma_lds<4, 4, 2>(Bs, GLD, As, GLD, wn * 64, wm * 64, acc);
;     __syncthreads();
;     G_STORE(ra1, rb1);
;     __syncthreads();
;     if (kt + 3 < nk) G_LOAD(ra1, rb1, kt + 3);
;     mfma_lds<4, 4, 2>(Bs, GLD, As, GLD, wn * 64, wm * 64, acc);
;   }
.LBB0_670:
	v_mov_b32_e32 v131, v195
	v_and_b32_e32 v143, 15, v131
	v_or_b32_e32 v144, v143, v140
	v_and_b32_e32 v148, 48, v131
	v_mul_u32_u24_e32 v131, 0x50, v144
	v_lshl_add_u32 v131, v131, 1, v148
	v_or_b32_e32 v143, v143, v142
	v_mad_u32_u24 v249, v143, s36, v148
	v_lshl_add_u64 v[132:133], v[132:133], 0, s[34:35]
	v_lshl_add_u64 v[134:135], v[134:135], 0, s[34:35]
	s_and_b64 vcc, exec, s[8:9]
	ds_read_b128 v[144:147], v131 offset:20480
	ds_read_b128 v[160:163], v249
	ds_read_b128 v[164:167], v249 offset:2560
	ds_read_b128 v[168:171], v249 offset:5120
	ds_read_b128 v[172:175], v249 offset:7680
	ds_read_b128 v[148:151], v131 offset:23040
	ds_read_b128 v[152:155], v131 offset:25600
	ds_read_b128 v[156:159], v131 offset:28160
	ds_read_b128 v[176:179], v249 offset:64
	ds_read_b128 v[180:183], v249 offset:2624
	ds_read_b128 v[188:191], v249 offset:5184
	ds_read_b128 v[236:239], v249 offset:7744
	ds_read_b128 v[240:243], v131 offset:20544
	ds_read_b128 v[244:247], v131 offset:23104
	s_waitcnt lgkmcnt(12)
	v_mfma_f32_16x16x32_bf16 v[126:129], v[144:147], v[160:163], v[126:129]
	s_waitcnt lgkmcnt(11)
	v_mfma_f32_16x16x32_bf16 v[122:125], v[144:147], v[164:167], v[122:125]
	s_waitcnt lgkmcnt(10)
	v_mfma_f32_16x16x32_bf16 v[118:121], v[144:147], v[168:171], v[118:121]
	s_waitcnt lgkmcnt(9)
	v_mfma_f32_16x16x32_bf16 v[114:117], v[144:147], v[172:175], v[114:117]
	ds_read_b128 v[144:147], v131 offset:25664
	s_waitcnt lgkmcnt(9)
	v_mfma_f32_16x16x32_bf16 v[110:113], v[148:151], v[160:163], v[110:113]
	v_mfma_f32_16x16x32_bf16 v[58:61], v[148:151], v[164:167], v[58:61]
	v_mfma_f32_16x16x32_bf16 v[38:41], v[148:151], v[168:171], v[38:41]
	v_mfma_f32_16x16x32_bf16 v[34:37], v[148:151], v[172:175], v[34:37]
	ds_read_b128 v[148:151], v131 offset:28224
	s_waitcnt lgkmcnt(9)
	v_mfma_f32_16x16x32_bf16 v[30:33], v[152:155], v[160:163], v[30:33]
	v_mfma_f32_16x16x32_bf16 v[26:29], v[152:155], v[164:167], v[26:29]
	v_mfma_f32_16x16x32_bf16 v[22:25], v[152:155], v[168:171], v[22:25]
	v_mfma_f32_16x16x32_bf16 v[18:21], v[152:155], v[172:175], v[18:21]
	s_waitcnt lgkmcnt(8)
	v_mfma_f32_16x16x32_bf16 v[14:17], v[156:159], v[160:163], v[14:17]
	v_mfma_f32_16x16x32_bf16 v[10:13], v[156:159], v[164:167], v[10:13]
	v_mfma_f32_16x16x32_bf16 v[6:9], v[156:159], v[168:171], v[6:9]
	v_mfma_f32_16x16x32_bf16 v[2:5], v[156:159], v[172:175], v[2:5]
	s_waitcnt lgkmcnt(0)
	v_mfma_f32_16x16x32_bf16 v[126:129], v[240:243], v[176:179], v[126:129]
	v_mfma_f32_16x16x32_bf16 v[122:125], v[240:243], v[180:183], v[122:125]
	v_mfma_f32_16x16x32_bf16 v[118:121], v[240:243], v[188:191], v[118:121]
	v_mfma_f32_16x16x32_bf16 v[114:117], v[240:243], v[236:239], v[114:117]
	v_mfma_f32_16x16x32_bf16 v[110:113], v[244:247], v[176:179], v[110:113]
	v_mfma_f32_16x16x32_bf16 v[58:61], v[244:247], v[180:183], v[58:61]
	v_mfma_f32_16x16x32_bf16 v[38:41], v[244:247], v[188:191], v[38:41]
	v_mfma_f32_16x16x32_bf16 v[34:37], v[244:247], v[236:239], v[34:37]
	v_mfma_f32_16x16x32_bf16 v[30:33], v[144:147], v[176:179], v[30:33]
	v_mfma_f32_16x16x32_bf16 v[26:29], v[144:147], v[180:183], v[26:29]
	v_mfma_f32_16x16x32_bf16 v[22:25], v[144:147], v[188:191], v[22:25]
	v_mfma_f32_16x16x32_bf16 v[18:21], v[144:147], v[236:239], v[18:21]
	v_mfma_f32_16x16x32_bf16 v[14:17], v[148:151], v[176:179], v[14:17]
	v_mfma_f32_16x16x32_bf16 v[10:13], v[148:151], v[180:183], v[10:13]
	v_mfma_f32_16x16x32_bf16 v[6:9], v[148:151], v[188:191], v[6:9]
	v_mfma_f32_16x16x32_bf16 v[2:5], v[148:151], v[236:239], v[2:5]
	s_cbranch_vccnz .LBB0_675

; DEV f32x4 mfma16(bf16x8 a, bf16x8 b, f32x4 c) { return __builtin_amdgcn_mfma_f32_16x16x32_bf16(a, b, c, 0, 0, 0); }
; #define G_LOAD(RA, RB, KT) { _Pragma("unroll") for (int i = 0; i < 4; i++) { \
;       RA[i] = *(const u32x4*)(Ap + (size_t)(i * 32) * lda + (KT) * 64); RB[i] = *(const u32x4*)(Bp + (size_t)(i * 32) * ldb + (KT) * 64); } }
; #define G_STORE(RA, RB) { _Pragma("unroll") for (int i = 0; i < 4; i++) { \
;       *(u32x4*)(As + (lrow + i * 32) * GLD + lcc * 8) = RA[i]; *(u32x4*)(Bs + (lrow + i * 32) * GLD + lcc * 8) = RB[i]; } }
; template <int TI, int TJ, int KS>
; DEV void mfma_lds(const bf16_t* Arows, int lda, const bf16_t* Brows, int ldb, int i0, int j0, f32x4 (&acc)[TI][TJ]) {
;     ...
;   for (int ks = 0; ks < KS; ks++) {
;     bf16x8 af[TI], bfr[TJ];
; #pragma unroll
;     for (int i = 0; i < TI; i++) af[i] = *(const bf16x8*)(Arows + (i0 + i * 16 + l15) * lda + ks * 32 + quad * 8);
; #pragma unroll
;     for (int j = 0; j < TJ; j++) bfr[j] = *(const bf16x8*)(Brows + (j0 + j * 16 + l15) * ldb + ks * 32 + quad * 8);
; #pragma unroll
;     for (int i = 0; i < TI; i++)
; #pragma unroll
;       for (int j = 0; j < TJ; j++) acc[i][j] = mfma16(af[i], bfr[j], acc[i][j]);
; template <class Epi>
; DEV void gemm_tile(const bf16_t* __restrict__ A, int lda, const bf16_t* __restrict__ Bt, int ldb, int K, int m0, int n0,
;                    Epi& epi, char* smem) {
;     ...
;   for (int kt = 0; kt < nk; kt += 2) {
;     __syncthreads();
;     G_STORE(ra0, rb0);
;     __syncthreads();
;     if (kt + 2 < nk) G_LOAD(ra0, rb0, kt + 2);
;     mfma_lds<4, 4, 2>(Bs, GLD, As, GLD, wn * 64, wm * 64, acc);
;     __syncthreads();
;     G_STORE(ra1, rb1);
;     __syncthreads();
;     if (kt + 3 < nk) G_LOAD(ra1, rb1, kt + 3);
;     mfma_lds<4, 4, 2>(Bs, GLD, As, GLD, wn * 64, wm * 64, acc);
;   }
.LBB0_673:
	v_mov_b32_e32 v131, v195
	s_cmp_gt_u32 s15, 12
	v_and_b32_e32 v143, 15, v131
	v_or_b32_e32 v144, v143, v140
	v_and_b32_e32 v148, 48, v131
	v_mul_u32_u24_e32 v131, 0x50, v144
	v_lshl_add_u32 v131, v131, 1, v148
	v_or_b32_e32 v143, v143, v142
	v_mad_u32_u24 v249, v143, s36, v148
	ds_read_b128 v[144:147], v131 offset:20480
	ds_read_b128 v[160:163], v249
	ds_read_b128 v[164:167], v249 offset:2560
	ds_read_b128 v[168:171], v249 offset:5120
	ds_read_b128 v[172:175], v249 offset:7680
	ds_read_b128 v[148:151], v131 offset:23040
	ds_read_b128 v[152:155], v131 offset:25600
	ds_read_b128 v[156:159], v131 offset:28160
	ds_read_b128 v[176:179], v249 offset:64
	ds_read_b128 v[180:183], v249 offset:2624
	ds_read_b128 v[188:191], v249 offset:5184
	ds_read_b128 v[236:239], v249 offset:7744
	ds_read_b128 v[240:243], v131 offset:20544
	ds_read_b128 v[244:247], v131 offset:23104
	s_waitcnt lgkmcnt(12)
	v_mfma_f32_16x16x32_bf16 v[126:129], v[144:147], v[160:163], v[126:129]
	s_waitcnt lgkmcnt(11)
	v_mfma_f32_16x16x32_bf16 v[122:125], v[144:147], v[164:167], v[122:125]
	s_waitcnt lgkmcnt(10)
	v_mfma_f32_16x16x32_bf16 v[118:121], v[144:147], v[168:171], v[118:121]
	s_waitcnt lgkmcnt(9)
	v_mfma_f32_16x16x32_bf16 v[114:117], v[144:147], v[172:175], v[114:117]
	ds_read_b128 v[144:147], v131 offset:25664
	s_waitcnt lgkmcnt(9)
	v_mfma_f32_16x16x32_bf16 v[110:113], v[148:151], v[160:163], v[110:113]
	v_mfma_f32_16x16x32_bf16 v[58:61], v[148:151], v[164:167], v[58:61]
	v_mfma_f32_16x16x32_bf16 v[38:41], v[148:151], v[168:171], v[38:41]
	v_mfma_f32_16x16x32_bf16 v[34:37], v[148:151], v[172:175], v[34:37]
	ds_read_b128 v[148:151], v131 offset:28224
	s_waitcnt lgkmcnt(9)
	v_mfma_f32_16x16x32_bf16 v[30:33], v[152:155], v[160:163], v[30:33]
	v_mfma_f32_16x16x32_bf16 v[26:29], v[152:155], v[164:167], v[26:29]
	v_mfma_f32_16x16x32_bf16 v[22:25], v[152:155], v[168:171], v[22:25]
	v_mfma_f32_16x16x32_bf16 v[18:21], v[152:155], v[172:175], v[18:21]
	s_waitcnt lgkmcnt(8)
	v_mfma_f32_16x16x32_bf16 v[14:17], v[156:159], v[160:163], v[14:17]
	v_mfma_f32_16x16x32_bf16 v[10:13], v[156:159], v[164:167], v[10:13]
	v_mfma_f32_16x16x32_bf16 v[6:9], v[156:159], v[168:171], v[6:9]
	v_mfma_f32_16x16x32_bf16 v[2:5], v[156:159], v[172:175], v[2:5]
	s_waitcnt lgkmcnt(0)
	v_mfma_f32_16x16x32_bf16 v[126:129], v[240:243], v[176:179], v[126:129]
	s_barrier
	v_mfma_f32_16x16x32_bf16 v[122:125], v[240:243], v[180:183], v[122:125]
	s_waitcnt vmcnt(8)
	ds_write_b128 v130, v[46:49]
	v_mfma_f32_16x16x32_bf16 v[118:121], v[240:243], v[188:191], v[118:121]
	ds_write_b128 v130, v[54:57] offset:20480
	v_mfma_f32_16x16x32_bf16 v[114:117], v[240:243], v[236:239], v[114:117]
	ds_write_b128 v130, v[66:69] offset:5120
	v_mfma_f32_16x16x32_bf16 v[110:113], v[244:247], v[176:179], v[110:113]
	ds_write_b128 v130, v[74:77] offset:25600
	v_mfma_f32_16x16x32_bf16 v[58:61], v[244:247], v[180:183], v[58:61]
	ds_write_b128 v130, v[82:85] offset:10240
	v_mfma_f32_16x16x32_bf16 v[38:41], v[244:247], v[188:191], v[38:41]
	ds_write_b128 v130, v[90:93] offset:30720
	v_mfma_f32_16x16x32_bf16 v[34:37], v[244:247], v[236:239], v[34:37]
	ds_write_b128 v130, v[98:101] offset:15360
	v_mfma_f32_16x16x32_bf16 v[30:33], v[144:147], v[176:179], v[30:33]
	ds_write_b128 v130, v[106:109] offset:35840
	v_mfma_f32_16x16x32_bf16 v[26:29], v[144:147], v[180:183], v[26:29]
	v_mfma_f32_16x16x32_bf16 v[22:25], v[144:147], v[188:191], v[22:25]
	s_waitcnt lgkmcnt(0)
	s_barrier
	v_mfma_f32_16x16x32_bf16 v[18:21], v[144:147], v[236:239], v[18:21]
	v_mfma_f32_16x16x32_bf16 v[14:17], v[148:151], v[176:179], v[14:17]
	v_mfma_f32_16x16x32_bf16 v[10:13], v[148:151], v[180:183], v[10:13]
	v_mfma_f32_16x16x32_bf16 v[6:9], v[148:151], v[188:191], v[6:9]
	v_mfma_f32_16x16x32_bf16 v[2:5], v[148:151], v[236:239], v[2:5]
	s_cbranch_scc1 .LBB0_670
	v_add_co_u32_e32 v46, vcc, 0x19700000, v138
	s_nop 1
	v_addc_co_u32_e32 v47, vcc, 0, v139, vcc
	v_add_co_u32_e32 v54, vcc, 0xa6e0000, v136
	global_load_dwordx4 v[46:49], v[46:47], off offset:384
	s_nop 0
	v_addc_co_u32_e32 v55, vcc, 0, v137, vcc
	v_add_co_u32_e32 v66, vcc, 0x19711000, v138
	global_load_dwordx4 v[54:57], v[54:55], off offset:384
	s_nop 0
	v_addc_co_u32_e32 v67, vcc, 0, v139, vcc
	v_add_co_u32_e32 v74, vcc, 0xa6f1000, v136
	global_load_dwordx4 v[66:69], v[66:67], off offset:384
	s_nop 0
	v_addc_co_u32_e32 v75, vcc, 0, v137, vcc
	v_add_co_u32_e32 v82, vcc, 0x19722000, v138
	global_load_dwordx4 v[74:77], v[74:75], off offset:384
	s_nop 0
	v_addc_co_u32_e32 v83, vcc, 0, v139, vcc
	v_add_co_u32_e32 v90, vcc, 0xa702000, v136
	global_load_dwordx4 v[82:85], v[82:83], off offset:384
	s_nop 0
	v_addc_co_u32_e32 v91, vcc, 0, v137, vcc
	v_add_co_u32_e32 v98, vcc, 0x19733000, v138
	global_load_dwordx4 v[90:93], v[90:91], off offset:384
	s_nop 0
	v_addc_co_u32_e32 v99, vcc, 0, v139, vcc
	v_add_co_u32_e32 v106, vcc, 0xa713000, v136
	global_load_dwordx4 v[98:101], v[98:99], off offset:384
	s_nop 0
	v_addc_co_u32_e32 v107, vcc, 0, v137, vcc
	global_load_dwordx4 v[106:109], v[106:107], off offset:384
	s_branch .LBB0_670

; DEV f32x4 mfma16(bf16x8 a, bf16x8 b, f32x4 c) { return __builtin_amdgcn_mfma_f32_16x16x32_bf16(a, b, c, 0, 0, 0); }
; #define G_LOAD(RA, RB, KT) { _Pragma("unroll") for (int i = 0; i < 4; i++) { \
;       RA[i] = *(const u32x4*)(Ap + (size_t)(i * 32) * lda + (KT) * 64); RB[i] = *(const u32x4*)(Bp + (size_t)(i * 32) * ldb + (KT) * 64); } }
; #define G_STORE(RA, RB) { _Pragma("unroll") for (int i = 0; i < 4; i++) { \
;       *(u32x4*)(As + (lrow + i * 32) * GLD + lcc * 8) = RA[i]; *(u32x4*)(Bs + (lrow + i * 32) * GLD + lcc * 8) = RB[i]; } }
; template <int TI, int TJ, int KS>
; DEV void mfma_lds(const bf16_t* Arows, int lda, const bf16_t* Brows, int ldb, int i0, int j0, f32x4 (&acc)[TI][TJ]) {
;     ...
;   for (int ks = 0; ks < KS; ks++) {
;     bf16x8 af[TI], bfr[TJ];
; #pragma unroll
;     for (int i = 0; i < TI; i++) af[i] = *(const bf16x8*)(Arows + (i0 + i * 16 + l15) * lda + ks * 32 + quad * 8);
; #pragma unroll
;     for (int j = 0; j < TJ; j++) bfr[j] = *(const bf16x8*)(Brows + (j0 + j * 16 + l15) * ldb + ks * 32 + quad * 8);
; #pragma unroll
;     for (int i = 0; i < TI; i++)
; #pragma unroll
;       for (int j = 0; j < TJ; j++) acc[i][j] = mfma16(af[i], bfr[j], acc[i][j]);
; template <class Epi>
; DEV void gemm_tile(const bf16_t* __restrict__ A, int lda, const bf16_t* __restrict__ Bt, int ldb, int K, int m0, int n0,
;                    Epi& epi, char* smem) {
;     ...
;   for (int kt = 0; kt < nk; kt += 2) {
;     __syncthreads();
;     G_STORE(ra0, rb0);
;     __syncthreads();
;     if (kt + 2 < nk) G_LOAD(ra0, rb0, kt + 2);
;     mfma_lds<4, 4, 2>(Bs, GLD, As, GLD, wn * 64, wm * 64, acc);
;     __syncthreads();
;     G_STORE(ra1, rb1);
;     __syncthreads();
;     if (kt + 3 < nk) G_LOAD(ra1, rb1, kt + 3);
;     mfma_lds<4, 4, 2>(Bs, GLD, As, GLD, wn * 64, wm * 64, acc);
;   }
.LBB0_1038:
	v_mov_b32_e32 v131, v195
	v_and_b32_e32 v143, 15, v131
	v_or_b32_e32 v144, v143, v141
	v_and_b32_e32 v148, 48, v131
	v_mul_u32_u24_e32 v131, 0x50, v144
	v_lshl_add_u32 v131, v131, 1, v148
	v_or_b32_e32 v143, v143, v142
	v_mad_u32_u24 v249, v143, s36, v148
	v_lshl_add_u64 v[132:133], v[132:133], 0, s[34:35]
	v_lshl_add_u64 v[134:135], v[134:135], 0, s[34:35]
	s_and_b64 vcc, exec, s[8:9]
	ds_read_b128 v[148:151], v131 offset:20480
	ds_read_b128 v[164:167], v249
	ds_read_b128 v[168:171], v249 offset:2560
	ds_read_b128 v[172:175], v249 offset:5120
	ds_read_b128 v[176:179], v249 offset:7680
	ds_read_b128 v[152:155], v131 offset:23040
	ds_read_b128 v[156:159], v131 offset:25600
	ds_read_b128 v[160:163], v131 offset:28160
	ds_read_b128 v[180:183], v249 offset:64
	ds_read_b128 v[184:187], v249 offset:2624
	ds_read_b128 v[188:191], v249 offset:5184
	ds_read_b128 v[236:239], v249 offset:7744
	ds_read_b128 v[240:243], v131 offset:20544
	ds_read_b128 v[244:247], v131 offset:23104
	s_waitcnt lgkmcnt(12)
	v_mfma_f32_16x16x32_bf16 v[114:117], v[148:151], v[164:167], v[114:117]
	s_waitcnt lgkmcnt(11)
	v_mfma_f32_16x16x32_bf16 v[126:129], v[148:151], v[168:171], v[126:129]
	s_waitcnt lgkmcnt(10)
	v_mfma_f32_16x16x32_bf16 v[122:125], v[148:151], v[172:175], v[122:125]
	s_waitcnt lgkmcnt(9)
	v_mfma_f32_16x16x32_bf16 v[118:121], v[148:151], v[176:179], v[118:121]
	ds_read_b128 v[148:151], v131 offset:25664
	s_waitcnt lgkmcnt(9)
	v_mfma_f32_16x16x32_bf16 v[110:113], v[152:155], v[164:167], v[110:113]
	v_mfma_f32_16x16x32_bf16 v[106:109], v[152:155], v[168:171], v[106:109]
	v_mfma_f32_16x16x32_bf16 v[102:105], v[152:155], v[172:175], v[102:105]
	v_mfma_f32_16x16x32_bf16 v[98:101], v[152:155], v[176:179], v[98:101]
	ds_read_b128 v[152:155], v131 offset:28224
	s_waitcnt lgkmcnt(9)
	v_mfma_f32_16x16x32_bf16 v[94:97], v[156:159], v[164:167], v[94:97]
	v_mfma_f32_16x16x32_bf16 v[82:85], v[156:159], v[168:171], v[82:85]
	v_mfma_f32_16x16x32_bf16 v[78:81], v[156:159], v[172:175], v[78:81]
	v_mfma_f32_16x16x32_bf16 v[70:73], v[156:159], v[176:179], v[70:73]
	s_waitcnt lgkmcnt(8)
	v_mfma_f32_16x16x32_bf16 v[86:89], v[160:163], v[164:167], v[86:89]
	v_mfma_f32_16x16x32_bf16 v[74:77], v[160:163], v[168:171], v[74:77]
	v_mfma_f32_16x16x32_bf16 v[66:69], v[160:163], v[172:175], v[66:69]
	v_mfma_f32_16x16x32_bf16 v[90:93], v[160:163], v[176:179], v[90:93]
	s_waitcnt lgkmcnt(0)
	v_mfma_f32_16x16x32_bf16 v[114:117], v[240:243], v[180:183], v[114:117]
	v_mfma_f32_16x16x32_bf16 v[126:129], v[240:243], v[184:187], v[126:129]
	v_mfma_f32_16x16x32_bf16 v[122:125], v[240:243], v[188:191], v[122:125]
	v_mfma_f32_16x16x32_bf16 v[118:121], v[240:243], v[236:239], v[118:121]
	v_mfma_f32_16x16x32_bf16 v[110:113], v[244:247], v[180:183], v[110:113]
	v_mfma_f32_16x16x32_bf16 v[106:109], v[244:247], v[184:187], v[106:109]
	v_mfma_f32_16x16x32_bf16 v[102:105], v[244:247], v[188:191], v[102:105]
	v_mfma_f32_16x16x32_bf16 v[98:101], v[244:247], v[236:239], v[98:101]
	v_mfma_f32_16x16x32_bf16 v[94:97], v[148:151], v[180:183], v[94:97]
	v_mfma_f32_16x16x32_bf16 v[82:85], v[148:151], v[184:187], v[82:85]
	v_mfma_f32_16x16x32_bf16 v[78:81], v[148:151], v[188:191], v[78:81]
	v_mfma_f32_16x16x32_bf16 v[70:73], v[148:151], v[236:239], v[70:73]
	v_mfma_f32_16x16x32_bf16 v[86:89], v[152:155], v[180:183], v[86:89]
	v_mfma_f32_16x16x32_bf16 v[74:77], v[152:155], v[184:187], v[74:77]
	v_mfma_f32_16x16x32_bf16 v[66:69], v[152:155], v[188:191], v[66:69]
	v_mfma_f32_16x16x32_bf16 v[90:93], v[152:155], v[236:239], v[90:93]
	s_cbranch_vccnz .LBB0_1043

; DEV f32x4 mfma16(bf16x8 a, bf16x8 b, f32x4 c) { return __builtin_amdgcn_mfma_f32_16x16x32_bf16(a, b, c, 0, 0, 0); }
; #define G_LOAD(RA, RB, KT) { _Pragma("unroll") for (int i = 0; i < 4; i++) { \
;       RA[i] = *(const u32x4*)(Ap + (size_t)(i * 32) * lda + (KT) * 64); RB[i] = *(const u32x4*)(Bp + (size_t)(i * 32) * ldb + (KT) * 64); } }
; #define G_STORE(RA, RB) { _Pragma("unroll") for (int i = 0; i < 4; i++) { \
;       *(u32x4*)(As + (lrow + i * 32) * GLD + lcc * 8) = RA[i]; *(u32x4*)(Bs + (lrow + i * 32) * GLD + lcc * 8) = RB[i]; } }
; template <int TI, int TJ, int KS>
; DEV void mfma_lds(const bf16_t* Arows, int lda, const bf16_t* Brows, int ldb, int i0, int j0, f32x4 (&acc)[TI][TJ]) {
;     ...
;   for (int ks = 0; ks < KS; ks++) {
;     bf16x8 af[TI], bfr[TJ];
; #pragma unroll
;     for (int i = 0; i < TI; i++) af[i] = *(const bf16x8*)(Arows + (i0 + i * 16 + l15) * lda + ks * 32 + quad * 8);
; #pragma unroll
;     for (int j = 0; j < TJ; j++) bfr[j] = *(const bf16x8*)(Brows + (j0 + j * 16 + l15) * ldb + ks * 32 + quad * 8);
; #pragma unroll
;     for (int i = 0; i < TI; i++)
; #pragma unroll
;       for (int j = 0; j < TJ; j++) acc[i][j] = mfma16(af[i], bfr[j], acc[i][j]);
; template <class Epi>
; DEV void gemm_tile(const bf16_t* __restrict__ A, int lda, const bf16_t* __restrict__ Bt, int ldb, int K, int m0, int n0,
;                    Epi& epi, char* smem) {
;     ...
;   for (int kt = 0; kt < nk; kt += 2) {
;     __syncthreads();
;     G_STORE(ra0, rb0);
;     __syncthreads();
;     if (kt + 2 < nk) G_LOAD(ra0, rb0, kt + 2);
;     mfma_lds<4, 4, 2>(Bs, GLD, As, GLD, wn * 64, wm * 64, acc);
;     __syncthreads();
;     G_STORE(ra1, rb1);
;     __syncthreads();
;     if (kt + 3 < nk) G_LOAD(ra1, rb1, kt + 3);
;     mfma_lds<4, 4, 2>(Bs, GLD, As, GLD, wn * 64, wm * 64, acc);
;   }
.LBB0_1041:
	v_mov_b32_e32 v131, v195
	s_cmp_gt_u32 s14, 12
	v_and_b32_e32 v143, 15, v131
	v_or_b32_e32 v144, v143, v141
	v_and_b32_e32 v148, 48, v131
	v_mul_u32_u24_e32 v131, 0x50, v144
	v_lshl_add_u32 v131, v131, 1, v148
	v_or_b32_e32 v143, v143, v142
	v_mad_u32_u24 v249, v143, s36, v148
	ds_read_b128 v[148:151], v131 offset:20480
	ds_read_b128 v[164:167], v249
	ds_read_b128 v[168:171], v249 offset:2560
	ds_read_b128 v[172:175], v249 offset:5120
	ds_read_b128 v[176:179], v249 offset:7680
	ds_read_b128 v[152:155], v131 offset:23040
	ds_read_b128 v[156:159], v131 offset:25600
	ds_read_b128 v[160:163], v131 offset:28160
	ds_read_b128 v[180:183], v249 offset:64
	ds_read_b128 v[184:187], v249 offset:2624
	ds_read_b128 v[188:191], v249 offset:5184
	ds_read_b128 v[236:239], v249 offset:7744
	ds_read_b128 v[240:243], v131 offset:20544
	ds_read_b128 v[244:247], v131 offset:23104
	s_waitcnt lgkmcnt(12)
	v_mfma_f32_16x16x32_bf16 v[114:117], v[148:151], v[164:167], v[114:117]
	s_waitcnt lgkmcnt(11)
	v_mfma_f32_16x16x32_bf16 v[126:129], v[148:151], v[168:171], v[126:129]
	s_waitcnt lgkmcnt(10)
	v_mfma_f32_16x16x32_bf16 v[122:125], v[148:151], v[172:175], v[122:125]
	s_waitcnt lgkmcnt(9)
	v_mfma_f32_16x16x32_bf16 v[118:121], v[148:151], v[176:179], v[118:121]
	ds_read_b128 v[148:151], v131 offset:25664
	s_waitcnt lgkmcnt(9)
	v_mfma_f32_16x16x32_bf16 v[110:113], v[152:155], v[164:167], v[110:113]
	v_mfma_f32_16x16x32_bf16 v[106:109], v[152:155], v[168:171], v[106:109]
	v_mfma_f32_16x16x32_bf16 v[102:105], v[152:155], v[172:175], v[102:105]
	v_mfma_f32_16x16x32_bf16 v[98:101], v[152:155], v[176:179], v[98:101]
	ds_read_b128 v[152:155], v131 offset:28224
	s_waitcnt lgkmcnt(9)
	v_mfma_f32_16x16x32_bf16 v[94:97], v[156:159], v[164:167], v[94:97]
	v_mfma_f32_16x16x32_bf16 v[82:85], v[156:159], v[168:171], v[82:85]
	v_mfma_f32_16x16x32_bf16 v[78:81], v[156:159], v[172:175], v[78:81]
	v_mfma_f32_16x16x32_bf16 v[70:73], v[156:159], v[176:179], v[70:73]
	s_waitcnt lgkmcnt(8)
	v_mfma_f32_16x16x32_bf16 v[86:89], v[160:163], v[164:167], v[86:89]
	v_mfma_f32_16x16x32_bf16 v[74:77], v[160:163], v[168:171], v[74:77]
	v_mfma_f32_16x16x32_bf16 v[66:69], v[160:163], v[172:175], v[66:69]
	v_mfma_f32_16x16x32_bf16 v[90:93], v[160:163], v[176:179], v[90:93]
	s_waitcnt lgkmcnt(0)
	v_mfma_f32_16x16x32_bf16 v[114:117], v[240:243], v[180:183], v[114:117]
	s_barrier
	v_mfma_f32_16x16x32_bf16 v[126:129], v[240:243], v[184:187], v[126:129]
	s_waitcnt vmcnt(8)
	ds_write_b128 v130, v[6:9]
	v_mfma_f32_16x16x32_bf16 v[122:125], v[240:243], v[188:191], v[122:125]
	ds_write_b128 v130, v[14:17] offset:20480
	v_mfma_f32_16x16x32_bf16 v[118:121], v[240:243], v[236:239], v[118:121]
	ds_write_b128 v130, v[22:25] offset:5120
	v_mfma_f32_16x16x32_bf16 v[110:113], v[244:247], v[180:183], v[110:113]
	ds_write_b128 v130, v[30:33] offset:25600
	v_mfma_f32_16x16x32_bf16 v[106:109], v[244:247], v[184:187], v[106:109]
	ds_write_b128 v130, v[38:41] offset:10240
	v_mfma_f32_16x16x32_bf16 v[102:105], v[244:247], v[188:191], v[102:105]
	ds_write_b128 v130, v[46:49] offset:30720
	v_mfma_f32_16x16x32_bf16 v[98:101], v[244:247], v[236:239], v[98:101]
	ds_write_b128 v130, v[54:57] offset:15360
	v_mfma_f32_16x16x32_bf16 v[94:97], v[148:151], v[180:183], v[94:97]
	ds_write_b128 v130, v[62:65] offset:35840
	v_mfma_f32_16x16x32_bf16 v[82:85], v[148:151], v[184:187], v[82:85]
	v_mfma_f32_16x16x32_bf16 v[78:81], v[148:151], v[188:191], v[78:81]
	s_waitcnt lgkmcnt(0)
	s_barrier
	v_mfma_f32_16x16x32_bf16 v[70:73], v[148:151], v[236:239], v[70:73]
	v_mfma_f32_16x16x32_bf16 v[86:89], v[152:155], v[180:183], v[86:89]
	v_mfma_f32_16x16x32_bf16 v[74:77], v[152:155], v[184:187], v[74:77]
	v_mfma_f32_16x16x32_bf16 v[66:69], v[152:155], v[188:191], v[66:69]
	v_mfma_f32_16x16x32_bf16 v[90:93], v[152:155], v[236:239], v[90:93]
	s_cbranch_scc1 .LBB0_1038
	v_add_co_u32_e32 v6, vcc, 0x4200000, v138
	s_nop 1
	v_addc_co_u32_e32 v7, vcc, 0, v139, vcc
	v_add_co_u32_e32 v14, vcc, 0xa300000, v136
	global_load_dwordx4 v[6:9], v[6:7], off offset:384
	s_nop 0
	v_addc_co_u32_e32 v15, vcc, 0, v137, vcc
	v_add_co_u32_e32 v22, vcc, 0x4211000, v138
	global_load_dwordx4 v[14:17], v[14:15], off offset:384
	s_nop 0
	v_addc_co_u32_e32 v23, vcc, 0, v139, vcc
	v_add_co_u32_e32 v30, vcc, 0xa311000, v136
	global_load_dwordx4 v[22:25], v[22:23], off offset:384
	s_nop 0
	v_addc_co_u32_e32 v31, vcc, 0, v137, vcc
	v_add_co_u32_e32 v38, vcc, 0x4222000, v138
	global_load_dwordx4 v[30:33], v[30:31], off offset:384
	s_nop 0
	v_addc_co_u32_e32 v39, vcc, 0, v139, vcc
	v_add_co_u32_e32 v46, vcc, 0xa322000, v136
	global_load_dwordx4 v[38:41], v[38:39], off offset:384
	s_nop 0
	v_addc_co_u32_e32 v47, vcc, 0, v137, vcc
	v_add_co_u32_e32 v54, vcc, 0x4233000, v138
	global_load_dwordx4 v[46:49], v[46:47], off offset:384
	s_nop 0
	v_addc_co_u32_e32 v55, vcc, 0, v139, vcc
	v_add_co_u32_e32 v62, vcc, 0xa333000, v136
	global_load_dwordx4 v[54:57], v[54:55], off offset:384
	s_nop 0
	v_addc_co_u32_e32 v63, vcc, 0, v137, vcc
	global_load_dwordx4 v[62:65], v[62:63], off offset:384
	s_branch .LBB0_1038
